# in-proj epilogue fully hand-written (all tile classes except gate/pad columns): DPP quad transpose, LDS-transposed row-contiguous stores for P / cache outputs / key-blocked transposed copies, axial ro
# speedup vs baseline: 1.0180x; 1.0165x over previous
.LBB0_7:
	s_add_i32 s18, s18, 1
	s_cmp_ge_i32 s18, s81
	s_cbranch_scc0 .LBB0_8
	s_endpgm

.LBB0_296:
	s_add_u32 s0, s60, 0x8748000
	s_addc_u32 s1, s61, 0
	s_lshl_b32 s6, s12, 6
	s_and_b32 s6, s6, 0x3c0
	s_lshl_b32 s8, s36, 4
	v_and_b32_e32 v8, 15, v16
	s_add_i32 s37, s8, s6
	v_or_b32_e32 v86, s37, v8
	v_add_u32_e32 v76, s20, v86
	v_mov_b64_e32 v[2:3], s[0:1]
	s_movk_i32 s48, 0x1a20
	v_mad_i64_i32 v[78:79], s[22:23], v76, s48, v[2:3]
	s_lshl_b32 s27, s26, 6
	s_lshl_b32 s22, s26, 7
	s_mul_i32 s44, s20, 0x1a20
	s_mul_hi_u32 s19, s20, 0x1a20
	s_add_u32 s0, s0, s44
	s_addc_u32 s1, s1, s19
	s_add_u32 s0, s0, s22
	s_mov_b32 s23, s21
	s_addc_u32 s1, s1, 0
	v_ashrrev_i32_e32 v102, 4, v16
	v_lshl_add_u64 v[2:3], v[78:79], 0, s[22:23]
	s_add_u32 s22, s0, 0x1400
	s_mov_b64 s[16:17], 0x1200
	v_lshlrev_b32_e32 v88, 3, v102
	s_addc_u32 s23, s1, 0
	s_lshl_b64 s[0:1], s[20:21], 9
	s_lshl_b32 s20, s26, 12
	v_lshl_add_u64 v[84:85], v[2:3], 0, s[16:17]
	v_ashrrev_i32_e32 v89, 31, v88
	s_add_u32 s6, s60, s0
	v_ashrrev_i32_e32 v6, 3, v16
	v_lshl_add_u64 v[2:3], v[88:89], 1, v[84:85]
	v_lshl_add_u32 v0, v86, 2, s11
	s_addc_u32 s13, s61, s1
	v_add_u32_e32 v9, s8, v6
	s_waitcnt lgkmcnt(0)
	s_barrier
	global_load_dwordx4 v[36:39], v[2:3], off
	global_load_dwordx4 v[40:43], v[2:3], off offset:64
	ds_read2st64_b32 v[82:83], v0 offset0:16 offset1:32
	ds_read2st64_b32 v[80:81], v0 offset0:64 offset1:80
	s_add_u32 s6, s6, s20
	v_and_b32_e32 v7, 2, v6
	v_lshrrev_b32_e32 v0, 1, v9
	s_addc_u32 s13, s13, 0
	v_and_or_b32 v0, v0, 12, v7
	s_add_u32 s6, s6, 0xb778000
	v_lshrrev_b32_e32 v0, 1, v0
	s_addc_u32 s42, s13, 0
	v_bitop3_b32 v0, v0, v16, 7 bitop3:0x78
	v_mov_b64_e32 v[2:3], s[22:23]
	s_lshl_b32 s13, s36, 11
	s_lshl_b32 s45, s36, 1
	v_mad_i64_i32 v[4:5], s[22:23], v9, s48, v[2:3]
	v_lshlrev_b32_e32 v0, 4, v0
	s_add_i32 s8, s11, s13
	v_lshl_add_u64 v[4:5], v[4:5], 0, v[0:1]
	s_add_i32 m0, s8, 0x6000
	s_or_b32 s43, s45, 1
	global_load_lds_dwordx4 v[4:5], off
	v_lshl_add_u32 v4, s43, 3, v6
	v_mad_i64_i32 v[2:3], s[22:23], v4, s48, v[2:3]
	s_lshr_b32 s22, s36, 31
	s_bfe_i32 s23, s36, 0x1001e
	s_add_i32 s22, s36, s22
	s_lshr_b32 s36, s23, 30
	s_add_i32 s23, s45, s36
	v_lshrrev_b32_e32 v5, 1, v4
	s_lshl_b32 s14, s43, 10
	s_ashr_i32 s22, s22, 1
	s_and_b32 s23, s23, 0x7ffffc
	v_and_or_b32 v5, v5, 12, v7
	s_add_i32 s46, s11, s14
	s_sub_i32 s38, s45, s23
	s_ashr_i32 s23, s22, 31
	v_lshrrev_b32_e32 v5, 1, v5
	s_add_i32 m0, s46, 0x6000
	s_lshl_b64 s[22:23], s[22:23], 14
	v_bitop3_b32 v5, v5, v16, 7 bitop3:0x78
	s_add_u32 s40, s6, s22
	v_lshlrev_b32_e32 v4, 4, v5
	v_mov_b32_e32 v5, v1
	s_addc_u32 s41, s42, s23
	s_lshl_b32 s38, s38, 9
	v_lshl_add_u64 v[2:3], v[2:3], 0, v[4:5]
	s_ashr_i32 s39, s38, 31
	global_load_lds_dwordx4 v[2:3], off
	v_lshlrev_b32_e32 v2, 3, v16
	s_lshl_b64 s[38:39], s[38:39], 1
	v_ashrrev_i32_e32 v3, 31, v2
	s_add_u32 s40, s40, s38
	s_addc_u32 s41, s41, s39
	v_lshlrev_b64 v[2:3], 1, v[2:3]
	s_add_i32 m0, s8, 0x8000
	s_add_i32 s8, s43, s36
	v_lshl_add_u64 v[6:7], s[40:41], 0, v[2:3]
	s_ashr_i32 s40, s8, 2
	s_and_b32 s8, s8, -4
	s_ashr_i32 s41, s40, 31
	s_sub_i32 s36, s43, s8
	s_lshl_b64 s[40:41], s[40:41], 14
	s_add_u32 s6, s6, s40
	s_addc_u32 s47, s42, s41
	s_lshl_b32 s42, s36, 9
	s_ashr_i32 s43, s42, 31
	s_lshl_b64 s[42:43], s[42:43], 1
	s_add_u32 s42, s6, s42
	s_addc_u32 s43, s47, s43
	global_load_lds_dwordx4 v[6:7], off
	v_lshl_add_u64 v[6:7], s[42:43], 0, v[2:3]
	s_add_i32 m0, s46, 0x8000
	s_or_b32 s6, s37, 15
	global_load_lds_dwordx4 v[6:7], off
	s_or_b32 s22, s22, s20
	s_add_u32 s22, s22, s0
	s_addc_u32 s23, s23, s1
	s_add_u32 s22, s22, s38
	s_addc_u32 s23, s23, s39
	v_readlane_b32 s16, v255, 6
	s_add_u32 s22, s16, s22
	v_readlane_b32 s17, v255, 7
	s_addc_u32 s23, s17, s23
	s_or_b32 s20, s40, s20
	s_add_u32 s20, s20, s0
	v_lshl_add_u64 v[90:91], s[22:23], 0, v[2:3]
	s_addc_u32 s22, s41, s1
	s_sub_i32 s0, s45, s8
	s_lshl_b32 s0, s0, 9
	s_bitset1_b32 s0, 9
	s_ashr_i32 s1, s0, 31
	s_lshl_b64 s[0:1], s[0:1], 1
	s_add_u32 s0, s20, s0
	s_addc_u32 s1, s22, s1
	s_add_u32 s0, s16, s0
	v_lshlrev_b32_e32 v6, 1, v16
	v_and_b32_e32 v7, 3, v16
	s_addc_u32 s1, s17, s1
	v_and_or_b32 v6, v6, 24, v7
	v_lshl_add_u64 v[92:93], s[0:1], 0, v[2:3]
	s_lshl_b32 s0, s12, 3
	v_lshlrev_b32_e32 v106, 7, v6
	v_lshrrev_b32_e32 v6, 1, v16
	s_and_b32 s0, s0, 0x180
	v_bitop3_b32 v7, v6, v102, 7 bitop3:0x6c
	s_add_u32 s0, s0, s44
	v_lshlrev_b32_e32 v107, 4, v7
	v_add_u32_e32 v7, 4, v102
	s_addc_u32 s1, 0, s19
	v_bitop3_b32 v6, v6, v7, 7 bitop3:0x6c
	v_mov_b64_e32 v[2:3], s[0:1]
	v_lshlrev_b32_e32 v108, 4, v6
	v_mad_i64_i32 v[6:7], s[0:1], v9, s48, v[2:3]
	v_lshl_add_u64 v[6:7], v[6:7], 0, v[0:1]
	v_add_u32_e32 v0, 8, v9
	v_readlane_b32 s16, v255, 8
	v_mad_i64_i32 v[2:3], s[0:1], v0, s48, v[2:3]
	v_readlane_b32 s17, v255, 9
	v_lshl_add_u64 v[2:3], v[2:3], 0, v[4:5]
	s_waitcnt vmcnt(0)
	v_lshl_add_u32 v104, v102, 5, s11
	v_lshl_add_u64 v[96:97], s[16:17], 0, v[2:3]
	v_mov_b32_e32 v2, v1
	v_mov_b32_e32 v3, v1
	v_and_b32_e32 v105, -16, v16
	v_lshlrev_b32_e32 v103, 6, v8
	v_lshl_add_u64 v[94:95], s[16:17], 0, v[6:7]
	v_mov_b32_e32 v0, v1
	v_mov_b64_e32 v[22:23], v[2:3]
	v_mov_b64_e32 v[26:27], v[2:3]
	v_mov_b64_e32 v[30:31], v[2:3]
	v_mov_b64_e32 v[34:35], v[2:3]
	v_mov_b64_e32 v[6:7], v[2:3]
	v_mov_b64_e32 v[10:11], v[2:3]
	v_mov_b64_e32 v[14:15], v[2:3]
	v_mov_b64_e32 v[18:19], v[2:3]
	v_ashrrev_i32_e32 v77, 31, v76
	v_mov_b32_e32 v87, v86
	v_mov_b32_e32 v89, v86
	v_mov_b32_e32 v100, 0
	s_mov_b32 s19, 63
	s_movk_i32 s20, 0x4000
	v_mov_b32_e32 v109, v104
	v_mov_b64_e32 v[20:21], v[0:1]
	v_mov_b64_e32 v[24:25], v[0:1]
	v_mov_b64_e32 v[28:29], v[0:1]
	v_mov_b64_e32 v[32:33], v[0:1]
	v_mov_b64_e32 v[4:5], v[0:1]
	v_mov_b64_e32 v[8:9], v[0:1]
	v_mov_b64_e32 v[12:13], v[0:1]
	v_mov_b64_e32 v[16:17], v[0:1]
	v_mov_b32_e32 v101, 0
	s_waitcnt vmcnt(0) lgkmcnt(0)
	s_barrier
	s_branch .LBB0_298
.Ltramp_7:
	s_branch .LBB0_7
.LBB0_297:
	s_waitcnt vmcnt(0)
	s_add_i32 s19, s19, 64
	s_addk_i32 s20, 0x4000
	v_lshl_add_u64 v[90:91], v[90:91], 0, s[24:25]
	v_lshl_add_u64 v[92:93], v[92:93], 0, s[24:25]
	v_lshl_add_u64 v[94:95], v[94:95], 0, s[74:75]
	v_lshl_add_u64 v[96:97], v[96:97], 0, s[74:75]
	s_cmpk_eq_i32 s19, 0x3ff
	v_add_u32_e32 v109, 0x100, v109
	s_waitcnt vmcnt(0) lgkmcnt(0)
	s_barrier
	s_cbranch_scc1 .LBB0_308

.LBB0_347:
	s_mul_hi_u32 s20, s19, 0xaaaaaaab
	s_lshr_b32 s20, s20, 1
	s_mul_i32 s20, s20, 0x24000
	s_waitcnt lgkmcnt(0)
	v_mfma_f32_16x16x32_bf16 v[82:85], v[26:29], v[22:25], v[82:85]
	v_add_u32_e32 v191, s13, v122
	s_mul_hi_u32 s23, s14, 0xaaaaaaab
	s_lshr_b32 s23, s23, 1
	v_mfma_f32_16x16x32_bf16 v[78:81], v[26:29], v[18:21], v[78:81]
	s_mul_i32 s23, s23, 0x24000
	v_subrev_u32_e32 v250, s23, v182
	v_subrev_u32_e32 v251, s23, v201
	v_mfma_f32_16x16x32_bf16 v[74:77], v[26:29], v[10:13], v[74:77]
	v_subrev_u32_e32 v252, s23, v202
	v_mfma_f32_16x16x32_bf16 v[70:73], v[26:29], v[6:9], v[70:73]
	v_subrev_u32_e32 v26, s20, v181
	v_mfma_f32_16x16x32_bf16 v[66:69], v[14:17], v[22:25], v[66:69]
	v_mfma_f32_16x16x32_bf16 v[62:65], v[14:17], v[18:21], v[62:65]
	v_mfma_f32_16x16x32_bf16 v[58:61], v[14:17], v[10:13], v[58:61]
	v_mfma_f32_16x16x32_bf16 v[54:57], v[14:17], v[6:9], v[54:57]
	v_subrev_u32_e32 v14, s20, v203
	v_add_u32_e32 v16, v191, v26
	v_add_u32_e32 v14, v191, v14
	v_mfma_f32_16x16x32_bf16 v[38:41], v[30:33], v[22:25], v[38:41]
	v_subrev_u32_e32 v15, s23, v204
	v_mfma_f32_16x16x32_bf16 v[50:53], v[2:5], v[22:25], v[50:53]
	ds_read_b128 v[22:25], v16
	ds_read_b128 v[222:225], v16 offset:2048
	ds_read_b128 v[226:229], v16 offset:4096
	ds_read_b128 v[230:233], v16 offset:6144
	ds_read_b128 v[234:237], v14 offset:32768
	ds_read_b128 v[238:241], v14 offset:34816
	ds_read_b128 v[242:245], v14 offset:36864
	ds_read_b128 v[246:249], v14 offset:38912
	v_mfma_f32_16x16x32_bf16 v[90:93], v[30:33], v[18:21], v[90:93]
	v_mfma_f32_16x16x32_bf16 v[86:89], v[30:33], v[10:13], v[86:89]
	v_mfma_f32_16x16x32_bf16 v[94:97], v[30:33], v[6:9], v[94:97]
	v_mfma_f32_16x16x32_bf16 v[46:49], v[2:5], v[18:21], v[46:49]
	v_mfma_f32_16x16x32_bf16 v[42:45], v[2:5], v[10:13], v[42:45]
	v_mfma_f32_16x16x32_bf16 v[34:37], v[2:5], v[6:9], v[34:37]
	s_add_i32 s20, s6, 4
	s_mul_i32 s23, s20, 0xab
	s_bfe_u32 s23, s23, 0x70009
	s_mul_i32 s23, s23, 3
	s_sub_i32 s20, s20, s23
	s_and_b32 s20, s20, 0xff
	s_mul_i32 s20, s20, 0xc000
	s_waitcnt vmcnt(6)
	v_add_u32_e32 v2, v191, v15
	v_add_u32_e32 v6, v191, v252
	s_waitcnt lgkmcnt(0)
	v_mfma_f32_16x16x32_bf16 v[82:85], v[222:225], v[234:237], v[82:85]
	s_add_i32 s23, s20, s11
	s_waitcnt lgkmcnt(0)
	s_barrier
	v_mfma_f32_16x16x32_bf16 v[78:81], v[222:225], v[238:241], v[78:81]
	ds_read_b128 v[30:33], v2
	ds_read_b128 v[26:29], v2 offset:2048
	ds_read_b128 v[14:17], v2 offset:4096
	ds_read_b128 v[2:5], v2 offset:6144
	v_add_u32_e32 v7, v191, v251
	v_mfma_f32_16x16x32_bf16 v[74:77], v[222:225], v[242:245], v[74:77]
	s_mov_b32 m0, s23
	s_mov_b64 s[34:35], 0x180
	s_add_i32 s20, s20, s12
	v_mfma_f32_16x16x32_bf16 v[70:73], v[222:225], v[246:249], v[70:73]
	v_lshl_add_u64 v[222:223], v[118:119], 0, v[102:103]
	v_lshl_add_u64 v[224:225], v[222:223], 0, s[84:85]
	s_add_i32 s19, s19, 1
	v_mfma_f32_16x16x32_bf16 v[38:41], v[22:25], v[234:237], v[38:41]
	v_mfma_f32_16x16x32_bf16 v[90:93], v[22:25], v[238:241], v[90:93]
	v_mfma_f32_16x16x32_bf16 v[86:89], v[22:25], v[242:245], v[86:89]
	v_mfma_f32_16x16x32_bf16 v[94:97], v[22:25], v[246:249], v[94:97]
	ds_read_b128 v[22:25], v6
	ds_read_b128 v[18:21], v7
	v_add_u32_e32 v6, v191, v250
	ds_read_b128 v[10:13], v6
	ds_read_b128 v[6:9], v6 offset:2048
	global_load_lds_dwordx4 v[224:225], off
	v_lshl_add_u64 v[224:225], v[222:223], 0, s[76:77]
	s_add_i32 m0, s23, 0x400
	v_mfma_f32_16x16x32_bf16 v[66:69], v[226:229], v[234:237], v[66:69]
	global_load_lds_dwordx4 v[224:225], off
	v_lshl_add_u64 v[224:225], v[222:223], 0, s[54:55]
	s_add_i32 m0, s23, 0x800
	v_lshl_add_u64 v[222:223], v[222:223], 0, s[68:69]
	global_load_lds_dwordx4 v[224:225], off
	s_add_i32 m0, s23, 0xc00
	v_mfma_f32_16x16x32_bf16 v[62:65], v[226:229], v[238:241], v[62:65]
	global_load_lds_dwordx4 v[222:223], off
	v_lshl_add_u64 v[222:223], v[120:121], 0, v[102:103]
	v_lshl_add_u64 v[224:225], v[222:223], 0, s[34:35]
	s_add_i32 m0, s20, 0x8000
	s_mov_b64 s[34:35], 0x4180
	global_load_lds_dwordx4 v[224:225], off
	v_lshl_add_u64 v[222:223], v[222:223], 0, s[34:35]
	s_add_i32 m0, s20, 0x8400
	v_mfma_f32_16x16x32_bf16 v[58:61], v[226:229], v[242:245], v[58:61]
	global_load_lds_dwordx4 v[222:223], off
	v_mfma_f32_16x16x32_bf16 v[54:57], v[226:229], v[246:249], v[54:57]
	v_mfma_f32_16x16x32_bf16 v[50:53], v[230:233], v[234:237], v[50:53]
	v_mfma_f32_16x16x32_bf16 v[46:49], v[230:233], v[238:241], v[46:49]
	v_mfma_f32_16x16x32_bf16 v[42:45], v[230:233], v[242:245], v[42:45]
	v_mfma_f32_16x16x32_bf16 v[34:37], v[230:233], v[246:249], v[34:37]
	s_add_i32 s6, s6, 1
	s_add_i32 s13, s13, 0xc000
	s_add_i32 s14, s14, 1
	v_lshl_add_u64 v[118:119], v[118:119], 0, s[2:3]
	s_cmp_eq_u32 s13, 0x9c000
	v_lshl_add_u64 v[120:121], v[120:121], 0, s[2:3]
	s_cbranch_scc0 .LBB0_347
	s_waitcnt lgkmcnt(0)
	v_mfma_f32_16x16x32_bf16 v[38:41], v[30:33], v[22:25], v[38:41]
	v_mfma_f32_16x16x32_bf16 v[90:93], v[30:33], v[18:21], v[90:93]
	v_mfma_f32_16x16x32_bf16 v[86:89], v[30:33], v[10:13], v[86:89]
	v_mfma_f32_16x16x32_bf16 v[30:33], v[30:33], v[6:9], v[94:97]
	v_mfma_f32_16x16x32_bf16 v[82:85], v[26:29], v[22:25], v[82:85]
	v_mfma_f32_16x16x32_bf16 v[78:81], v[26:29], v[18:21], v[78:81]
	v_mfma_f32_16x16x32_bf16 v[74:77], v[26:29], v[10:13], v[74:77]
	v_mfma_f32_16x16x32_bf16 v[26:29], v[26:29], v[6:9], v[70:73]
	v_mfma_f32_16x16x32_bf16 v[66:69], v[14:17], v[22:25], v[66:69]
	v_mfma_f32_16x16x32_bf16 v[62:65], v[14:17], v[18:21], v[62:65]
	v_mfma_f32_16x16x32_bf16 v[58:61], v[14:17], v[10:13], v[58:61]
	v_mfma_f32_16x16x32_bf16 v[14:17], v[14:17], v[6:9], v[54:57]
	v_mfma_f32_16x16x32_bf16 v[22:25], v[2:5], v[22:25], v[50:53]
	v_mfma_f32_16x16x32_bf16 v[18:21], v[2:5], v[18:21], v[46:49]
	s_nop 2
	ds_read_b128 v[46:49], v205
	ds_read_b128 v[50:53], v206 offset:2048
	ds_read_b128 v[54:57], v206 offset:4096
	ds_read_b128 v[70:73], v206 offset:6144
	v_mfma_f32_16x16x32_bf16 v[10:13], v[2:5], v[10:13], v[42:45]
	s_nop 2
	ds_read_b128 v[42:45], v207 offset:32768
	ds_read_b128 v[94:97], v208 offset:34816
	ds_read_b128 v[118:121], v208 offset:36864
	ds_read_b128 v[222:225], v208 offset:38912
	v_mfma_f32_16x16x32_bf16 v[2:5], v[2:5], v[6:9], v[34:37]
	s_waitcnt lgkmcnt(0)
	v_mfma_f32_16x16x32_bf16 v[6:9], v[46:49], v[42:45], v[38:41]
	s_waitcnt vmcnt(6)
	s_waitcnt lgkmcnt(0)
	s_barrier
	v_mfma_f32_16x16x32_bf16 v[34:37], v[46:49], v[94:97], v[90:93]
	v_mfma_f32_16x16x32_bf16 v[38:41], v[46:49], v[118:121], v[86:89]
	s_nop 1
	v_add_u32_e32 v90, 0x20800, v212
	v_mfma_f32_16x16x32_bf16 v[30:33], v[46:49], v[222:225], v[30:33]
	v_mfma_f32_16x16x32_bf16 v[46:49], v[50:53], v[42:45], v[82:85]
	v_mfma_f32_16x16x32_bf16 v[78:81], v[50:53], v[94:97], v[78:81]
	v_mfma_f32_16x16x32_bf16 v[74:77], v[50:53], v[118:121], v[74:77]
	v_mfma_f32_16x16x32_bf16 v[26:29], v[50:53], v[222:225], v[26:29]
	v_mfma_f32_16x16x32_bf16 v[50:53], v[54:57], v[42:45], v[66:69]
	v_mfma_f32_16x16x32_bf16 v[62:65], v[54:57], v[94:97], v[62:65]
	v_mfma_f32_16x16x32_bf16 v[58:61], v[54:57], v[118:121], v[58:61]
	v_mfma_f32_16x16x32_bf16 v[14:17], v[54:57], v[222:225], v[14:17]
	v_add_u32_e32 v54, v180, v124
	ds_read_b128 v[54:57], v54
	ds_read_b128 v[66:69], v209 offset:2048
	v_mfma_f32_16x16x32_bf16 v[18:21], v[70:73], v[94:97], v[18:21]
	v_add_u32_e32 v94, 0x21000, v212
	v_mfma_f32_16x16x32_bf16 v[10:13], v[70:73], v[118:121], v[10:13]
	v_add_u32_e32 v118, 0x21800, v212
	v_mfma_f32_16x16x32_bf16 v[22:25], v[70:73], v[42:45], v[22:25]
	ds_read_b128 v[42:45], v209 offset:4096
	ds_read_b128 v[82:85], v209 offset:6144
	ds_read_b128 v[86:89], v211
	ds_read_b128 v[90:93], v90
	ds_read_b128 v[94:97], v94
	ds_read_b128 v[118:121], v118
	v_mfma_f32_16x16x32_bf16 v[2:5], v[70:73], v[222:225], v[2:5]
	s_waitcnt lgkmcnt(0)
	v_mfma_f32_16x16x32_bf16 v[50:53], v[42:45], v[86:89], v[50:53]
	v_mfma_f32_16x16x32_bf16 v[62:65], v[42:45], v[90:93], v[62:65]
	v_mfma_f32_16x16x32_bf16 v[58:61], v[42:45], v[94:97], v[58:61]
	v_mfma_f32_16x16x32_bf16 v[14:17], v[42:45], v[118:121], v[14:17]
	v_add_u32_e32 v42, v180, v128
	v_mfma_f32_16x16x32_bf16 v[6:9], v[54:57], v[86:89], v[6:9]
	v_mfma_f32_16x16x32_bf16 v[34:37], v[54:57], v[90:93], v[34:37]
	v_mfma_f32_16x16x32_bf16 v[38:41], v[54:57], v[94:97], v[38:41]
	v_mfma_f32_16x16x32_bf16 v[30:33], v[54:57], v[118:121], v[30:33]
	v_mfma_f32_16x16x32_bf16 v[46:49], v[66:69], v[86:89], v[46:49]
	v_mfma_f32_16x16x32_bf16 v[54:57], v[66:69], v[90:93], v[78:81]
	v_mfma_f32_16x16x32_bf16 v[70:73], v[66:69], v[94:97], v[74:77]
	v_mfma_f32_16x16x32_bf16 v[26:29], v[66:69], v[118:121], v[26:29]
	ds_read_b128 v[42:45], v42
	ds_read_b128 v[66:69], v213
	ds_read_b128 v[74:77], v214
	ds_read_b128 v[78:81], v215
	v_mfma_f32_16x16x32_bf16 v[22:25], v[82:85], v[86:89], v[22:25]
	v_mfma_f32_16x16x32_bf16 v[18:21], v[82:85], v[90:93], v[18:21]
	v_mfma_f32_16x16x32_bf16 v[10:13], v[82:85], v[94:97], v[10:13]
	ds_read_b128 v[86:89], v216
	ds_read_b128 v[90:93], v217
	ds_read_b128 v[94:97], v218
	ds_read_b128 v[222:225], v219
	v_mfma_f32_16x16x32_bf16 v[2:5], v[82:85], v[118:121], v[2:5]
	s_waitcnt vmcnt(0)
	s_waitcnt lgkmcnt(0)
	v_mfma_f32_16x16x32_bf16 v[6:9], v[42:45], v[86:89], v[6:9]
	s_waitcnt lgkmcnt(0)
	s_barrier
	v_mfma_f32_16x16x32_bf16 v[34:37], v[42:45], v[90:93], v[34:37]
	v_mfma_f32_16x16x32_bf16 v[38:41], v[42:45], v[94:97], v[38:41]
	v_mfma_f32_16x16x32_bf16 v[30:33], v[42:45], v[222:225], v[30:33]
	v_mfma_f32_16x16x32_bf16 v[42:45], v[66:69], v[86:89], v[46:49]
	v_mfma_f32_16x16x32_bf16 v[46:49], v[66:69], v[90:93], v[54:57]
	v_mfma_f32_16x16x32_bf16 v[54:57], v[66:69], v[94:97], v[70:73]
	v_mfma_f32_16x16x32_bf16 v[26:29], v[66:69], v[222:225], v[26:29]
	v_mfma_f32_16x16x32_bf16 v[50:53], v[74:77], v[86:89], v[50:53]
	v_mfma_f32_16x16x32_bf16 v[62:65], v[74:77], v[90:93], v[62:65]
	v_mfma_f32_16x16x32_bf16 v[58:61], v[74:77], v[94:97], v[58:61]
	v_mfma_f32_16x16x32_bf16 v[14:17], v[74:77], v[222:225], v[14:17]
	ds_read_b128 v[66:69], v212 offset:38912
	ds_read_b128 v[70:73], v212 offset:36864
	ds_read_b128 v[74:77], v212 offset:34816
	ds_read_b128 v[82:85], v210 offset:32768
	v_mfma_f32_16x16x32_bf16 v[22:25], v[78:81], v[86:89], v[22:25]
	v_mfma_f32_16x16x32_bf16 v[18:21], v[78:81], v[90:93], v[18:21]
	v_mfma_f32_16x16x32_bf16 v[10:13], v[78:81], v[94:97], v[10:13]
	ds_read_b128 v[86:89], v221 offset:6144
	ds_read_b128 v[90:93], v221 offset:4096
	ds_read_b128 v[94:97], v221 offset:2048
	ds_read_b128 v[118:121], v117
	v_mfma_f32_16x16x32_bf16 v[2:5], v[78:81], v[222:225], v[2:5]
	s_waitcnt lgkmcnt(0)
	v_mfma_f32_16x16x32_bf16 v[42:45], v[94:97], v[82:85], v[42:45]
	v_add_u32_e32 v78, v123, v128
	v_add_u32_e32 v117, v127, v128
	v_mfma_f32_16x16x32_bf16 v[46:49], v[94:97], v[74:77], v[46:49]
	v_mfma_f32_16x16x32_bf16 v[54:57], v[94:97], v[70:73], v[54:57]
	v_mfma_f32_16x16x32_bf16 v[26:29], v[94:97], v[66:69], v[26:29]
	v_add_u32_e32 v94, v126, v128
	v_mfma_f32_16x16x32_bf16 v[50:53], v[90:93], v[82:85], v[50:53]
	v_mfma_f32_16x16x32_bf16 v[62:65], v[90:93], v[74:77], v[62:65]
	v_mfma_f32_16x16x32_bf16 v[58:61], v[90:93], v[70:73], v[58:61]
	v_mfma_f32_16x16x32_bf16 v[14:17], v[90:93], v[66:69], v[14:17]
	v_add_u32_e32 v90, v125, v128
	v_mfma_f32_16x16x32_bf16 v[6:9], v[118:121], v[82:85], v[6:9]
	v_mfma_f32_16x16x32_bf16 v[34:37], v[118:121], v[74:77], v[34:37]
	v_mfma_f32_16x16x32_bf16 v[38:41], v[118:121], v[70:73], v[38:41]
	v_mfma_f32_16x16x32_bf16 v[30:33], v[118:121], v[66:69], v[30:33]
	v_mfma_f32_16x16x32_bf16 v[22:25], v[86:89], v[82:85], v[22:25]
	ds_read_b128 v[78:81], v78
	ds_read_b128 v[82:85], v90 offset:2048
	v_mfma_f32_16x16x32_bf16 v[18:21], v[86:89], v[74:77], v[18:21]
	ds_read_b128 v[74:77], v90 offset:4096
	ds_read_b128 v[90:93], v90 offset:6144
	v_mfma_f32_16x16x32_bf16 v[10:13], v[86:89], v[70:73], v[10:13]
	ds_read_b128 v[70:73], v94 offset:32768
	ds_read_b128 v[94:97], v117 offset:34816
	ds_read_b128 v[118:121], v117 offset:36864
	ds_read_b128 v[222:225], v117 offset:38912
	v_mfma_f32_16x16x32_bf16 v[2:5], v[86:89], v[66:69], v[2:5]
	s_waitcnt vmcnt(0)
	s_waitcnt lgkmcnt(0)
	s_waitcnt lgkmcnt(0)
	v_mfma_f32_16x16x32_bf16 v[6:9], v[78:81], v[70:73], v[6:9]
	s_barrier
	v_mfma_f32_16x16x32_bf16 v[34:37], v[78:81], v[94:97], v[34:37]
	v_mfma_f32_16x16x32_bf16 v[38:41], v[78:81], v[118:121], v[38:41]
	v_mfma_f32_16x16x32_bf16 v[30:33], v[78:81], v[222:225], v[30:33]
	v_mfma_f32_16x16x32_bf16 v[42:45], v[82:85], v[70:73], v[42:45]
	v_mfma_f32_16x16x32_bf16 v[46:49], v[82:85], v[94:97], v[46:49]
	v_mfma_f32_16x16x32_bf16 v[54:57], v[82:85], v[118:121], v[54:57]
	v_mfma_f32_16x16x32_bf16 v[26:29], v[82:85], v[222:225], v[26:29]
	v_mfma_f32_16x16x32_bf16 v[50:53], v[74:77], v[70:73], v[50:53]
	v_mfma_f32_16x16x32_bf16 v[62:65], v[74:77], v[94:97], v[62:65]
	v_mfma_f32_16x16x32_bf16 v[58:61], v[74:77], v[118:121], v[58:61]
	v_mfma_f32_16x16x32_bf16 v[14:17], v[74:77], v[222:225], v[14:17]
	v_mfma_f32_16x16x32_bf16 v[22:25], v[90:93], v[70:73], v[22:25]
	v_mfma_f32_16x16x32_bf16 v[18:21], v[90:93], v[94:97], v[18:21]
	v_mfma_f32_16x16x32_bf16 v[10:13], v[90:93], v[118:121], v[10:13]
	v_mfma_f32_16x16x32_bf16 v[2:5], v[90:93], v[222:225], v[2:5]
	s_waitcnt lgkmcnt(0)
	s_barrier
	v_mov_b32_e32 v230, s75
	v_mov_b32_e32 v231, 0xaaaaaaab
	v_mul_hi_u32 v231, v230, v231
	v_lshrrev_b32_e32 v231, 4, v231
	v_cmp_gt_u32_e32 vcc, 26, v231
	s_nop 4
	s_cmp_lg_u64 vcc, 0
	s_cbranch_scc0 .Lipe_fallback
	s_mul_hi_i32 s6, s75, 0x2aaaaaab
	s_lshr_b32 s13, s6, 31
	s_ashr_i32 s6, s6, 2
	s_add_i32 s6, s6, s13
	s_mul_i32 s13, s6, 24
	s_sub_i32 s13, s75, s13
	v_readfirstlane_b32 s14, v137
	s_lshr_b32 s14, s14, 6
	s_and_b32 s19, s14, 1
	s_lshr_b32 s20, s14, 1
	s_lshl_b32 s13, s13, 8
	s_lshl_b32 s20, s20, 6
	s_add_i32 s13, s13, s20
	s_lshl_b32 s6, s6, 7
	s_lshl_b32 s19, s19, 6
	s_add_i32 s6, s6, s19
	s_mul_i32 s14, s14, 0x4100
	s_lshr_b32 s20, s6, 8
	s_cmpk_lt_i32 s13, 0x1000
	s_cselect_b32 s19, 1, 0
	s_and_b32 s46, s13, 0xff
	s_add_i32 s47, s13, 0xfffff000
	s_and_b32 s47, s47, 0x3ff
	s_cmp_lg_u32 s19, 0
	s_cselect_b32 s46, s46, s47
	s_sub_i32 s47, s13, s46
	v_and_b32_e32 v221, 63, v137
	v_and_b32_e32 v222, 15, v221
	v_lshrrev_b32_e32 v223, 4, v221
	v_and_b32_e32 v224, 3, v222
	v_lshrrev_b32_e32 v225, 2, v222
	v_lshl_or_b32 v226, v223, 2, v224
	v_lshl_add_u32 v232, v221, 4, s14
	v_lshrrev_b32_e32 v236, 3, v221
	v_and_b32_e32 v237, 7, v221
	v_xor_b32_e32 v237, v237, v236
	s_mov_b32 s16, 0xd30
	s_lshr_b32 s16, s16, s20
	s_and_b32 s16, s16, 1
	s_cbranch_scc0 .Lipe_noT
	s_mov_b32 s22, 0xae78000
	s_mov_b32 s23, 9
	s_sub_i32 s26, s6, 1024
	s_add_i32 s27, s6, 0xfffff800
	s_cmp_eq_u32 s20, 8
	s_cselect_b32 s22, 0xb478000, s22
	s_cselect_b32 s23, 8, s23
	s_cselect_b32 s26, s27, s26
	s_add_i32 s27, s6, 0xfffff600
	s_cmp_eq_u32 s20, 10
	s_cselect_b32 s22, 0xba78000, s22
	s_cselect_b32 s23, 8, s23
	s_cselect_b32 s26, s27, s26
	s_add_i32 s27, s6, 0xfffff500
	s_cmp_eq_u32 s20, 11
	s_cselect_b32 s22, 0xb778000, s22
	s_cselect_b32 s23, 8, s23
	s_cselect_b32 s26, s27, s26
	s_lshl_b32 s27, s47, 1
	s_lshl_b32 s27, s27, s23
	s_add_i32 s22, s22, s27
	s_lshr_b32 s27, s46, 5
	s_lshl_b32 s27, s27, 6
	s_lshl_b32 s27, s27, s23
	s_add_i32 s22, s22, s27
	s_lshl_b32 s27, s26, 6
	s_add_i32 s22, s22, s27
	v_lshrrev_b32_e32 v233, 2, v237
	v_lshlrev_b32_e32 v233, 6, v233
	v_lshlrev_b32_e32 v233, s23, v233
	v_lshl_add_u32 v233, v236, 6, v233
	v_and_b32_e32 v234, 3, v237
	v_lshl_add_u32 v233, v234, 4, v233
	v_add_u32_e32 v233, s22, v233
	v_and_b32_e32 v227, 7, v222
	v_lshlrev_b32_e32 v227, 1, v227
	v_or_b32_e32 v228, 0, v223
	v_xor_b32_e32 v228, v228, v227
	v_lshlrev_b32_e32 v228, 3, v228
	v_lshl_add_u32 v228, v222, 7, v228
	v_add_u32_e32 v228, s14, v228
	v_or_b32_e32 v229, 4, v223
	v_xor_b32_e32 v229, v229, v227
	v_lshlrev_b32_e32 v229, 3, v229
	v_lshl_add_u32 v229, v222, 7, v229
	v_add_u32_e32 v229, s14, v229
	v_or_b32_e32 v230, 8, v223
	v_xor_b32_e32 v230, v230, v227
	v_lshlrev_b32_e32 v230, 3, v230
	v_lshl_add_u32 v230, v222, 7, v230
	v_add_u32_e32 v230, s14, v230
	v_or_b32_e32 v231, 12, v223
	v_xor_b32_e32 v231, v231, v227
	v_lshlrev_b32_e32 v231, 3, v231
	v_lshl_add_u32 v231, v222, 7, v231
	v_add_u32_e32 v231, s14, v231
	v_cvt_pk_bf16_f32 v66, v6, v7
	v_cvt_pk_bf16_f32 v67, v8, v9
	ds_write_b64 v228, v[66:67] offset:0
	v_cvt_pk_bf16_f32 v70, v34, v35
	v_cvt_pk_bf16_f32 v71, v36, v37
	ds_write_b64 v228, v[70:71] offset:2048
	v_cvt_pk_bf16_f32 v74, v38, v39
	v_cvt_pk_bf16_f32 v75, v40, v41
	ds_write_b64 v228, v[74:75] offset:4096
	v_cvt_pk_bf16_f32 v78, v30, v31
	v_cvt_pk_bf16_f32 v79, v32, v33
	ds_write_b64 v228, v[78:79] offset:6144
	v_cvt_pk_bf16_f32 v82, v42, v43
	v_cvt_pk_bf16_f32 v83, v44, v45
	ds_write_b64 v229, v[82:83] offset:0
	v_cvt_pk_bf16_f32 v86, v46, v47
	v_cvt_pk_bf16_f32 v87, v48, v49
	ds_write_b64 v229, v[86:87] offset:2048
	v_cvt_pk_bf16_f32 v90, v54, v55
	v_cvt_pk_bf16_f32 v91, v56, v57
	ds_write_b64 v229, v[90:91] offset:4096
	v_cvt_pk_bf16_f32 v94, v26, v27
	v_cvt_pk_bf16_f32 v95, v28, v29
	ds_write_b64 v229, v[94:95] offset:6144
	v_cvt_pk_bf16_f32 v66, v50, v51
	v_cvt_pk_bf16_f32 v67, v52, v53
	ds_write_b64 v230, v[66:67] offset:0
	v_cvt_pk_bf16_f32 v70, v62, v63
	v_cvt_pk_bf16_f32 v71, v64, v65
	ds_write_b64 v230, v[70:71] offset:2048
	v_cvt_pk_bf16_f32 v74, v58, v59
	v_cvt_pk_bf16_f32 v75, v60, v61
	ds_write_b64 v230, v[74:75] offset:4096
	v_cvt_pk_bf16_f32 v78, v14, v15
	v_cvt_pk_bf16_f32 v79, v16, v17
	ds_write_b64 v230, v[78:79] offset:6144
	v_cvt_pk_bf16_f32 v82, v22, v23
	v_cvt_pk_bf16_f32 v83, v24, v25
	ds_write_b64 v231, v[82:83] offset:0
	v_cvt_pk_bf16_f32 v86, v18, v19
	v_cvt_pk_bf16_f32 v87, v20, v21
	ds_write_b64 v231, v[86:87] offset:2048
	v_cvt_pk_bf16_f32 v90, v10, v11
	v_cvt_pk_bf16_f32 v91, v12, v13
	ds_write_b64 v231, v[90:91] offset:4096
	v_cvt_pk_bf16_f32 v94, v2, v3
	v_cvt_pk_bf16_f32 v95, v4, v5
	ds_write_b64 v231, v[94:95] offset:6144
	s_waitcnt lgkmcnt(0)
	ds_read_b128 v[66:69], v232 offset:0
	ds_read_b128 v[70:73], v232 offset:1024
	ds_read_b128 v[74:77], v232 offset:2048
	ds_read_b128 v[78:81], v232 offset:3072
	ds_read_b128 v[82:85], v232 offset:4096
	ds_read_b128 v[86:89], v232 offset:5120
	ds_read_b128 v[90:93], v232 offset:6144
	ds_read_b128 v[94:97], v232 offset:7168
	s_waitcnt lgkmcnt(7)
	global_store_dwordx4 v233, v[66:69], s[94:95]
	s_waitcnt lgkmcnt(6)
	v_add_u32_e32 v235, 0x200, v233
	global_store_dwordx4 v235, v[70:73], s[94:95]
	s_waitcnt lgkmcnt(5)
	v_add_u32_e32 v235, 0x400, v233
	global_store_dwordx4 v235, v[74:77], s[94:95]
	s_waitcnt lgkmcnt(4)
	v_add_u32_e32 v235, 0x600, v233
	global_store_dwordx4 v235, v[78:81], s[94:95]
	s_waitcnt lgkmcnt(3)
	v_add_u32_e32 v235, 0x800, v233
	global_store_dwordx4 v235, v[82:85], s[94:95]
	s_waitcnt lgkmcnt(2)
	v_add_u32_e32 v235, 0xa00, v233
	global_store_dwordx4 v235, v[86:89], s[94:95]
	s_waitcnt lgkmcnt(1)
	v_add_u32_e32 v235, 0xc00, v233
	global_store_dwordx4 v235, v[90:93], s[94:95]
	s_waitcnt lgkmcnt(0)
	v_add_u32_e32 v235, 0xe00, v233
	global_store_dwordx4 v235, v[94:97], s[94:95]
	s_nop 1
.Lipe_noT:
	s_mov_b32 s16, 0x16cf
	s_lshr_b32 s16, s16, s20
	s_and_b32 s16, s16, 1
	s_mov_b32 s17, 0x1bc
	s_lshr_b32 s17, s17, s20
	s_and_b32 s17, s17, s19
	s_or_b32 s22, s16, s17
	s_cmp_lg_u32 s22, 0
	s_cbranch_scc0 .LBB0_345
	s_mov_b32 s34, 0xaaaaaaaa
	s_mov_b32 s35, 0xaaaaaaaa
	s_mov_b32 s36, 0xcccccccc
	s_mov_b32 s37, 0xcccccccc
	s_nop 1
	v_mov_b32_dpp v66, v7 quad_perm:[1,0,3,2] row_mask:0xf bank_mask:0xf
	v_mov_b32_dpp v67, v6 quad_perm:[1,0,3,2] row_mask:0xf bank_mask:0xf
	v_mov_b32_dpp v68, v9 quad_perm:[1,0,3,2] row_mask:0xf bank_mask:0xf
	v_mov_b32_dpp v69, v8 quad_perm:[1,0,3,2] row_mask:0xf bank_mask:0xf
	v_cndmask_b32_e64 v6, v6, v66, s[34:35]
	v_cndmask_b32_e64 v7, v67, v7, s[34:35]
	v_cndmask_b32_e64 v8, v8, v68, s[34:35]
	v_cndmask_b32_e64 v9, v69, v9, s[34:35]
	s_nop 1
	v_mov_b32_dpp v68, v6 quad_perm:[2,3,0,1] row_mask:0xf bank_mask:0xf
	v_mov_b32_dpp v69, v7 quad_perm:[2,3,0,1] row_mask:0xf bank_mask:0xf
	v_mov_b32_dpp v66, v8 quad_perm:[2,3,0,1] row_mask:0xf bank_mask:0xf
	v_mov_b32_dpp v67, v9 quad_perm:[2,3,0,1] row_mask:0xf bank_mask:0xf
	v_cndmask_b32_e64 v6, v6, v66, s[36:37]
	v_cndmask_b32_e64 v7, v7, v67, s[36:37]
	v_cndmask_b32_e64 v8, v68, v8, s[36:37]
	v_cndmask_b32_e64 v9, v69, v9, s[36:37]
	s_nop 1
	v_mov_b32_dpp v66, v35 quad_perm:[1,0,3,2] row_mask:0xf bank_mask:0xf
	v_mov_b32_dpp v67, v34 quad_perm:[1,0,3,2] row_mask:0xf bank_mask:0xf
	v_mov_b32_dpp v68, v37 quad_perm:[1,0,3,2] row_mask:0xf bank_mask:0xf
	v_mov_b32_dpp v69, v36 quad_perm:[1,0,3,2] row_mask:0xf bank_mask:0xf
	v_cndmask_b32_e64 v34, v34, v66, s[34:35]
	v_cndmask_b32_e64 v35, v67, v35, s[34:35]
	v_cndmask_b32_e64 v36, v36, v68, s[34:35]
	v_cndmask_b32_e64 v37, v69, v37, s[34:35]
	s_nop 1
	v_mov_b32_dpp v68, v34 quad_perm:[2,3,0,1] row_mask:0xf bank_mask:0xf
	v_mov_b32_dpp v69, v35 quad_perm:[2,3,0,1] row_mask:0xf bank_mask:0xf
	v_mov_b32_dpp v66, v36 quad_perm:[2,3,0,1] row_mask:0xf bank_mask:0xf
	v_mov_b32_dpp v67, v37 quad_perm:[2,3,0,1] row_mask:0xf bank_mask:0xf
	v_cndmask_b32_e64 v34, v34, v66, s[36:37]
	v_cndmask_b32_e64 v35, v35, v67, s[36:37]
	v_cndmask_b32_e64 v36, v68, v36, s[36:37]
	v_cndmask_b32_e64 v37, v69, v37, s[36:37]
	s_nop 1
	v_mov_b32_dpp v66, v39 quad_perm:[1,0,3,2] row_mask:0xf bank_mask:0xf
	v_mov_b32_dpp v67, v38 quad_perm:[1,0,3,2] row_mask:0xf bank_mask:0xf
	v_mov_b32_dpp v68, v41 quad_perm:[1,0,3,2] row_mask:0xf bank_mask:0xf
	v_mov_b32_dpp v69, v40 quad_perm:[1,0,3,2] row_mask:0xf bank_mask:0xf
	v_cndmask_b32_e64 v38, v38, v66, s[34:35]
	v_cndmask_b32_e64 v39, v67, v39, s[34:35]
	v_cndmask_b32_e64 v40, v40, v68, s[34:35]
	v_cndmask_b32_e64 v41, v69, v41, s[34:35]
	s_nop 1
	v_mov_b32_dpp v68, v38 quad_perm:[2,3,0,1] row_mask:0xf bank_mask:0xf
	v_mov_b32_dpp v69, v39 quad_perm:[2,3,0,1] row_mask:0xf bank_mask:0xf
	v_mov_b32_dpp v66, v40 quad_perm:[2,3,0,1] row_mask:0xf bank_mask:0xf
	v_mov_b32_dpp v67, v41 quad_perm:[2,3,0,1] row_mask:0xf bank_mask:0xf
	v_cndmask_b32_e64 v38, v38, v66, s[36:37]
	v_cndmask_b32_e64 v39, v39, v67, s[36:37]
	v_cndmask_b32_e64 v40, v68, v40, s[36:37]
	v_cndmask_b32_e64 v41, v69, v41, s[36:37]
	s_nop 1
	v_mov_b32_dpp v66, v31 quad_perm:[1,0,3,2] row_mask:0xf bank_mask:0xf
	v_mov_b32_dpp v67, v30 quad_perm:[1,0,3,2] row_mask:0xf bank_mask:0xf
	v_mov_b32_dpp v68, v33 quad_perm:[1,0,3,2] row_mask:0xf bank_mask:0xf
	v_mov_b32_dpp v69, v32 quad_perm:[1,0,3,2] row_mask:0xf bank_mask:0xf
	v_cndmask_b32_e64 v30, v30, v66, s[34:35]
	v_cndmask_b32_e64 v31, v67, v31, s[34:35]
	v_cndmask_b32_e64 v32, v32, v68, s[34:35]
	v_cndmask_b32_e64 v33, v69, v33, s[34:35]
	s_nop 1
	v_mov_b32_dpp v68, v30 quad_perm:[2,3,0,1] row_mask:0xf bank_mask:0xf
	v_mov_b32_dpp v69, v31 quad_perm:[2,3,0,1] row_mask:0xf bank_mask:0xf
	v_mov_b32_dpp v66, v32 quad_perm:[2,3,0,1] row_mask:0xf bank_mask:0xf
	v_mov_b32_dpp v67, v33 quad_perm:[2,3,0,1] row_mask:0xf bank_mask:0xf
	v_cndmask_b32_e64 v30, v30, v66, s[36:37]
	v_cndmask_b32_e64 v31, v31, v67, s[36:37]
	v_cndmask_b32_e64 v32, v68, v32, s[36:37]
	v_cndmask_b32_e64 v33, v69, v33, s[36:37]
	s_nop 1
	v_mov_b32_dpp v66, v43 quad_perm:[1,0,3,2] row_mask:0xf bank_mask:0xf
	v_mov_b32_dpp v67, v42 quad_perm:[1,0,3,2] row_mask:0xf bank_mask:0xf
	v_mov_b32_dpp v68, v45 quad_perm:[1,0,3,2] row_mask:0xf bank_mask:0xf
	v_mov_b32_dpp v69, v44 quad_perm:[1,0,3,2] row_mask:0xf bank_mask:0xf
	v_cndmask_b32_e64 v42, v42, v66, s[34:35]
	v_cndmask_b32_e64 v43, v67, v43, s[34:35]
	v_cndmask_b32_e64 v44, v44, v68, s[34:35]
	v_cndmask_b32_e64 v45, v69, v45, s[34:35]
	s_nop 1
	v_mov_b32_dpp v68, v42 quad_perm:[2,3,0,1] row_mask:0xf bank_mask:0xf
	v_mov_b32_dpp v69, v43 quad_perm:[2,3,0,1] row_mask:0xf bank_mask:0xf
	v_mov_b32_dpp v66, v44 quad_perm:[2,3,0,1] row_mask:0xf bank_mask:0xf
	v_mov_b32_dpp v67, v45 quad_perm:[2,3,0,1] row_mask:0xf bank_mask:0xf
	v_cndmask_b32_e64 v42, v42, v66, s[36:37]
	v_cndmask_b32_e64 v43, v43, v67, s[36:37]
	v_cndmask_b32_e64 v44, v68, v44, s[36:37]
	v_cndmask_b32_e64 v45, v69, v45, s[36:37]
	s_nop 1
	v_mov_b32_dpp v66, v47 quad_perm:[1,0,3,2] row_mask:0xf bank_mask:0xf
	v_mov_b32_dpp v67, v46 quad_perm:[1,0,3,2] row_mask:0xf bank_mask:0xf
	v_mov_b32_dpp v68, v49 quad_perm:[1,0,3,2] row_mask:0xf bank_mask:0xf
	v_mov_b32_dpp v69, v48 quad_perm:[1,0,3,2] row_mask:0xf bank_mask:0xf
	v_cndmask_b32_e64 v46, v46, v66, s[34:35]
	v_cndmask_b32_e64 v47, v67, v47, s[34:35]
	v_cndmask_b32_e64 v48, v48, v68, s[34:35]
	v_cndmask_b32_e64 v49, v69, v49, s[34:35]
	s_nop 1
	v_mov_b32_dpp v68, v46 quad_perm:[2,3,0,1] row_mask:0xf bank_mask:0xf
	v_mov_b32_dpp v69, v47 quad_perm:[2,3,0,1] row_mask:0xf bank_mask:0xf
	v_mov_b32_dpp v66, v48 quad_perm:[2,3,0,1] row_mask:0xf bank_mask:0xf
	v_mov_b32_dpp v67, v49 quad_perm:[2,3,0,1] row_mask:0xf bank_mask:0xf
	v_cndmask_b32_e64 v46, v46, v66, s[36:37]
	v_cndmask_b32_e64 v47, v47, v67, s[36:37]
	v_cndmask_b32_e64 v48, v68, v48, s[36:37]
	v_cndmask_b32_e64 v49, v69, v49, s[36:37]
	s_nop 1
	v_mov_b32_dpp v66, v55 quad_perm:[1,0,3,2] row_mask:0xf bank_mask:0xf
	v_mov_b32_dpp v67, v54 quad_perm:[1,0,3,2] row_mask:0xf bank_mask:0xf
	v_mov_b32_dpp v68, v57 quad_perm:[1,0,3,2] row_mask:0xf bank_mask:0xf
	v_mov_b32_dpp v69, v56 quad_perm:[1,0,3,2] row_mask:0xf bank_mask:0xf
	v_cndmask_b32_e64 v54, v54, v66, s[34:35]
	v_cndmask_b32_e64 v55, v67, v55, s[34:35]
	v_cndmask_b32_e64 v56, v56, v68, s[34:35]
	v_cndmask_b32_e64 v57, v69, v57, s[34:35]
	s_nop 1
	v_mov_b32_dpp v68, v54 quad_perm:[2,3,0,1] row_mask:0xf bank_mask:0xf
	v_mov_b32_dpp v69, v55 quad_perm:[2,3,0,1] row_mask:0xf bank_mask:0xf
	v_mov_b32_dpp v66, v56 quad_perm:[2,3,0,1] row_mask:0xf bank_mask:0xf
	v_mov_b32_dpp v67, v57 quad_perm:[2,3,0,1] row_mask:0xf bank_mask:0xf
	v_cndmask_b32_e64 v54, v54, v66, s[36:37]
	v_cndmask_b32_e64 v55, v55, v67, s[36:37]
	v_cndmask_b32_e64 v56, v68, v56, s[36:37]
	v_cndmask_b32_e64 v57, v69, v57, s[36:37]
	s_nop 1
	v_mov_b32_dpp v66, v27 quad_perm:[1,0,3,2] row_mask:0xf bank_mask:0xf
	v_mov_b32_dpp v67, v26 quad_perm:[1,0,3,2] row_mask:0xf bank_mask:0xf
	v_mov_b32_dpp v68, v29 quad_perm:[1,0,3,2] row_mask:0xf bank_mask:0xf
	v_mov_b32_dpp v69, v28 quad_perm:[1,0,3,2] row_mask:0xf bank_mask:0xf
	v_cndmask_b32_e64 v26, v26, v66, s[34:35]
	v_cndmask_b32_e64 v27, v67, v27, s[34:35]
	v_cndmask_b32_e64 v28, v28, v68, s[34:35]
	v_cndmask_b32_e64 v29, v69, v29, s[34:35]
	s_nop 1
	v_mov_b32_dpp v68, v26 quad_perm:[2,3,0,1] row_mask:0xf bank_mask:0xf
	v_mov_b32_dpp v69, v27 quad_perm:[2,3,0,1] row_mask:0xf bank_mask:0xf
	v_mov_b32_dpp v66, v28 quad_perm:[2,3,0,1] row_mask:0xf bank_mask:0xf
	v_mov_b32_dpp v67, v29 quad_perm:[2,3,0,1] row_mask:0xf bank_mask:0xf
	v_cndmask_b32_e64 v26, v26, v66, s[36:37]
	v_cndmask_b32_e64 v27, v27, v67, s[36:37]
	v_cndmask_b32_e64 v28, v68, v28, s[36:37]
	v_cndmask_b32_e64 v29, v69, v29, s[36:37]
	s_nop 1
	v_mov_b32_dpp v66, v51 quad_perm:[1,0,3,2] row_mask:0xf bank_mask:0xf
	v_mov_b32_dpp v67, v50 quad_perm:[1,0,3,2] row_mask:0xf bank_mask:0xf
	v_mov_b32_dpp v68, v53 quad_perm:[1,0,3,2] row_mask:0xf bank_mask:0xf
	v_mov_b32_dpp v69, v52 quad_perm:[1,0,3,2] row_mask:0xf bank_mask:0xf
	v_cndmask_b32_e64 v50, v50, v66, s[34:35]
	v_cndmask_b32_e64 v51, v67, v51, s[34:35]
	v_cndmask_b32_e64 v52, v52, v68, s[34:35]
	v_cndmask_b32_e64 v53, v69, v53, s[34:35]
	s_nop 1
	v_mov_b32_dpp v68, v50 quad_perm:[2,3,0,1] row_mask:0xf bank_mask:0xf
	v_mov_b32_dpp v69, v51 quad_perm:[2,3,0,1] row_mask:0xf bank_mask:0xf
	v_mov_b32_dpp v66, v52 quad_perm:[2,3,0,1] row_mask:0xf bank_mask:0xf
	v_mov_b32_dpp v67, v53 quad_perm:[2,3,0,1] row_mask:0xf bank_mask:0xf
	v_cndmask_b32_e64 v50, v50, v66, s[36:37]
	v_cndmask_b32_e64 v51, v51, v67, s[36:37]
	v_cndmask_b32_e64 v52, v68, v52, s[36:37]
	v_cndmask_b32_e64 v53, v69, v53, s[36:37]
	s_nop 1
	v_mov_b32_dpp v66, v63 quad_perm:[1,0,3,2] row_mask:0xf bank_mask:0xf
	v_mov_b32_dpp v67, v62 quad_perm:[1,0,3,2] row_mask:0xf bank_mask:0xf
	v_mov_b32_dpp v68, v65 quad_perm:[1,0,3,2] row_mask:0xf bank_mask:0xf
	v_mov_b32_dpp v69, v64 quad_perm:[1,0,3,2] row_mask:0xf bank_mask:0xf
	v_cndmask_b32_e64 v62, v62, v66, s[34:35]
	v_cndmask_b32_e64 v63, v67, v63, s[34:35]
	v_cndmask_b32_e64 v64, v64, v68, s[34:35]
	v_cndmask_b32_e64 v65, v69, v65, s[34:35]
	s_nop 1
	v_mov_b32_dpp v68, v62 quad_perm:[2,3,0,1] row_mask:0xf bank_mask:0xf
	v_mov_b32_dpp v69, v63 quad_perm:[2,3,0,1] row_mask:0xf bank_mask:0xf
	v_mov_b32_dpp v66, v64 quad_perm:[2,3,0,1] row_mask:0xf bank_mask:0xf
	v_mov_b32_dpp v67, v65 quad_perm:[2,3,0,1] row_mask:0xf bank_mask:0xf
	v_cndmask_b32_e64 v62, v62, v66, s[36:37]
	v_cndmask_b32_e64 v63, v63, v67, s[36:37]
	v_cndmask_b32_e64 v64, v68, v64, s[36:37]
	v_cndmask_b32_e64 v65, v69, v65, s[36:37]
	s_nop 1
	v_mov_b32_dpp v66, v59 quad_perm:[1,0,3,2] row_mask:0xf bank_mask:0xf
	v_mov_b32_dpp v67, v58 quad_perm:[1,0,3,2] row_mask:0xf bank_mask:0xf
	v_mov_b32_dpp v68, v61 quad_perm:[1,0,3,2] row_mask:0xf bank_mask:0xf
	v_mov_b32_dpp v69, v60 quad_perm:[1,0,3,2] row_mask:0xf bank_mask:0xf
	v_cndmask_b32_e64 v58, v58, v66, s[34:35]
	v_cndmask_b32_e64 v59, v67, v59, s[34:35]
	v_cndmask_b32_e64 v60, v60, v68, s[34:35]
	v_cndmask_b32_e64 v61, v69, v61, s[34:35]
	s_nop 1
	v_mov_b32_dpp v68, v58 quad_perm:[2,3,0,1] row_mask:0xf bank_mask:0xf
	v_mov_b32_dpp v69, v59 quad_perm:[2,3,0,1] row_mask:0xf bank_mask:0xf
	v_mov_b32_dpp v66, v60 quad_perm:[2,3,0,1] row_mask:0xf bank_mask:0xf
	v_mov_b32_dpp v67, v61 quad_perm:[2,3,0,1] row_mask:0xf bank_mask:0xf
	v_cndmask_b32_e64 v58, v58, v66, s[36:37]
	v_cndmask_b32_e64 v59, v59, v67, s[36:37]
	v_cndmask_b32_e64 v60, v68, v60, s[36:37]
	v_cndmask_b32_e64 v61, v69, v61, s[36:37]
	s_nop 1
	v_mov_b32_dpp v66, v15 quad_perm:[1,0,3,2] row_mask:0xf bank_mask:0xf
	v_mov_b32_dpp v67, v14 quad_perm:[1,0,3,2] row_mask:0xf bank_mask:0xf
	v_mov_b32_dpp v68, v17 quad_perm:[1,0,3,2] row_mask:0xf bank_mask:0xf
	v_mov_b32_dpp v69, v16 quad_perm:[1,0,3,2] row_mask:0xf bank_mask:0xf
	v_cndmask_b32_e64 v14, v14, v66, s[34:35]
	v_cndmask_b32_e64 v15, v67, v15, s[34:35]
	v_cndmask_b32_e64 v16, v16, v68, s[34:35]
	v_cndmask_b32_e64 v17, v69, v17, s[34:35]
	s_nop 1
	v_mov_b32_dpp v68, v14 quad_perm:[2,3,0,1] row_mask:0xf bank_mask:0xf
	v_mov_b32_dpp v69, v15 quad_perm:[2,3,0,1] row_mask:0xf bank_mask:0xf
	v_mov_b32_dpp v66, v16 quad_perm:[2,3,0,1] row_mask:0xf bank_mask:0xf
	v_mov_b32_dpp v67, v17 quad_perm:[2,3,0,1] row_mask:0xf bank_mask:0xf
	v_cndmask_b32_e64 v14, v14, v66, s[36:37]
	v_cndmask_b32_e64 v15, v15, v67, s[36:37]
	v_cndmask_b32_e64 v16, v68, v16, s[36:37]
	v_cndmask_b32_e64 v17, v69, v17, s[36:37]
	s_nop 1
	v_mov_b32_dpp v66, v23 quad_perm:[1,0,3,2] row_mask:0xf bank_mask:0xf
	v_mov_b32_dpp v67, v22 quad_perm:[1,0,3,2] row_mask:0xf bank_mask:0xf
	v_mov_b32_dpp v68, v25 quad_perm:[1,0,3,2] row_mask:0xf bank_mask:0xf
	v_mov_b32_dpp v69, v24 quad_perm:[1,0,3,2] row_mask:0xf bank_mask:0xf
	v_cndmask_b32_e64 v22, v22, v66, s[34:35]
	v_cndmask_b32_e64 v23, v67, v23, s[34:35]
	v_cndmask_b32_e64 v24, v24, v68, s[34:35]
	v_cndmask_b32_e64 v25, v69, v25, s[34:35]
	s_nop 1
	v_mov_b32_dpp v68, v22 quad_perm:[2,3,0,1] row_mask:0xf bank_mask:0xf
	v_mov_b32_dpp v69, v23 quad_perm:[2,3,0,1] row_mask:0xf bank_mask:0xf
	v_mov_b32_dpp v66, v24 quad_perm:[2,3,0,1] row_mask:0xf bank_mask:0xf
	v_mov_b32_dpp v67, v25 quad_perm:[2,3,0,1] row_mask:0xf bank_mask:0xf
	v_cndmask_b32_e64 v22, v22, v66, s[36:37]
	v_cndmask_b32_e64 v23, v23, v67, s[36:37]
	v_cndmask_b32_e64 v24, v68, v24, s[36:37]
	v_cndmask_b32_e64 v25, v69, v25, s[36:37]
	s_nop 1
	v_mov_b32_dpp v66, v19 quad_perm:[1,0,3,2] row_mask:0xf bank_mask:0xf
	v_mov_b32_dpp v67, v18 quad_perm:[1,0,3,2] row_mask:0xf bank_mask:0xf
	v_mov_b32_dpp v68, v21 quad_perm:[1,0,3,2] row_mask:0xf bank_mask:0xf
	v_mov_b32_dpp v69, v20 quad_perm:[1,0,3,2] row_mask:0xf bank_mask:0xf
	v_cndmask_b32_e64 v18, v18, v66, s[34:35]
	v_cndmask_b32_e64 v19, v67, v19, s[34:35]
	v_cndmask_b32_e64 v20, v20, v68, s[34:35]
	v_cndmask_b32_e64 v21, v69, v21, s[34:35]
	s_nop 1
	v_mov_b32_dpp v68, v18 quad_perm:[2,3,0,1] row_mask:0xf bank_mask:0xf
	v_mov_b32_dpp v69, v19 quad_perm:[2,3,0,1] row_mask:0xf bank_mask:0xf
	v_mov_b32_dpp v66, v20 quad_perm:[2,3,0,1] row_mask:0xf bank_mask:0xf
	v_mov_b32_dpp v67, v21 quad_perm:[2,3,0,1] row_mask:0xf bank_mask:0xf
	v_cndmask_b32_e64 v18, v18, v66, s[36:37]
	v_cndmask_b32_e64 v19, v19, v67, s[36:37]
	v_cndmask_b32_e64 v20, v68, v20, s[36:37]
	v_cndmask_b32_e64 v21, v69, v21, s[36:37]
	s_nop 1
	v_mov_b32_dpp v66, v11 quad_perm:[1,0,3,2] row_mask:0xf bank_mask:0xf
	v_mov_b32_dpp v67, v10 quad_perm:[1,0,3,2] row_mask:0xf bank_mask:0xf
	v_mov_b32_dpp v68, v13 quad_perm:[1,0,3,2] row_mask:0xf bank_mask:0xf
	v_mov_b32_dpp v69, v12 quad_perm:[1,0,3,2] row_mask:0xf bank_mask:0xf
	v_cndmask_b32_e64 v10, v10, v66, s[34:35]
	v_cndmask_b32_e64 v11, v67, v11, s[34:35]
	v_cndmask_b32_e64 v12, v12, v68, s[34:35]
	v_cndmask_b32_e64 v13, v69, v13, s[34:35]
	s_nop 1
	v_mov_b32_dpp v68, v10 quad_perm:[2,3,0,1] row_mask:0xf bank_mask:0xf
	v_mov_b32_dpp v69, v11 quad_perm:[2,3,0,1] row_mask:0xf bank_mask:0xf
	v_mov_b32_dpp v66, v12 quad_perm:[2,3,0,1] row_mask:0xf bank_mask:0xf
	v_mov_b32_dpp v67, v13 quad_perm:[2,3,0,1] row_mask:0xf bank_mask:0xf
	v_cndmask_b32_e64 v10, v10, v66, s[36:37]
	v_cndmask_b32_e64 v11, v11, v67, s[36:37]
	v_cndmask_b32_e64 v12, v68, v12, s[36:37]
	v_cndmask_b32_e64 v13, v69, v13, s[36:37]
	s_nop 1
	v_mov_b32_dpp v66, v3 quad_perm:[1,0,3,2] row_mask:0xf bank_mask:0xf
	v_mov_b32_dpp v67, v2 quad_perm:[1,0,3,2] row_mask:0xf bank_mask:0xf
	v_mov_b32_dpp v68, v5 quad_perm:[1,0,3,2] row_mask:0xf bank_mask:0xf
	v_mov_b32_dpp v69, v4 quad_perm:[1,0,3,2] row_mask:0xf bank_mask:0xf
	v_cndmask_b32_e64 v2, v2, v66, s[34:35]
	v_cndmask_b32_e64 v3, v67, v3, s[34:35]
	v_cndmask_b32_e64 v4, v4, v68, s[34:35]
	v_cndmask_b32_e64 v5, v69, v5, s[34:35]
	s_nop 1
	v_mov_b32_dpp v68, v2 quad_perm:[2,3,0,1] row_mask:0xf bank_mask:0xf
	v_mov_b32_dpp v69, v3 quad_perm:[2,3,0,1] row_mask:0xf bank_mask:0xf
	v_mov_b32_dpp v66, v4 quad_perm:[2,3,0,1] row_mask:0xf bank_mask:0xf
	v_mov_b32_dpp v67, v5 quad_perm:[2,3,0,1] row_mask:0xf bank_mask:0xf
	v_cndmask_b32_e64 v2, v2, v66, s[36:37]
	v_cndmask_b32_e64 v3, v3, v67, s[36:37]
	v_cndmask_b32_e64 v4, v68, v4, s[36:37]
	v_cndmask_b32_e64 v5, v69, v5, s[36:37]
	s_cmp_lg_u32 s17, 0
	s_cbranch_scc0 .Lipe_noO
	s_mov_b32 s22, 6291456
	s_mov_b32 s23, 7
	s_add_i32 s26, s6, 0xfffffe00
	s_add_i32 s27, s6, 0xfffffc00
	s_cmp_ge_u32 s20, 4
	s_cselect_b32 s22, 14680064, s22
	s_cselect_b32 s26, s27, s26
	s_add_i32 s27, s6, 0xfffff900
	s_cmp_eq_u32 s20, 7
	s_cselect_b32 s22, 23068672, s22
	s_cselect_b32 s23, 6, s23
	s_cselect_b32 s26, s27, s26
	s_add_i32 s27, s6, 0xfffff800
	s_cmp_eq_u32 s20, 8
	s_cselect_b32 s22, 27262976, s22
	s_cselect_b32 s23, 6, s23
	s_cselect_b32 s26, s27, s26
	v_readlane_b32 s27, v255, 40
	s_lshr_b32 s48, s47, 8
	s_lshl_b32 s48, s48, 4
	s_lshl_b32 s27, s27, 2
	s_add_i32 s48, s48, s27
	s_lshr_b32 s27, s26, s23
	s_add_i32 s48, s48, s27
	s_lshl_b32 s48, s48, 8
	s_add_i32 s48, s48, s46
	s_lshl_b32 s48, s48, s23
	s_lshl_b32 s27, s27, s23
	s_sub_i32 s27, s26, s27
	s_add_i32 s48, s48, s27
	s_add_i32 s48, s48, s22
	s_lshl_b32 s48, s48, 2
	v_lshlrev_b32_e32 v233, 1, v223
	v_xor_b32_e32 v233, v233, v222
	v_lshlrev_b32_e32 v233, 4, v233
	s_add_i32 s27, s23, 2
	v_lshlrev_b32_e32 v234, s27, v223
	v_add3_u32 v233, v233, v234, s48
	s_lshl_b32 s49, 16, s23
	v_and_b32_e32 v227, 3, v226
	v_lshlrev_b32_e32 v227, 1, v227
	v_or_b32_e32 v228, 0, v225
	v_xor_b32_e32 v228, v228, v227
	v_lshlrev_b32_e32 v228, 4, v228
	v_lshl_add_u32 v228, v226, 8, v228
	v_add_u32_e32 v228, s14, v228
	v_or_b32_e32 v229, 4, v225
	v_xor_b32_e32 v229, v229, v227
	v_lshlrev_b32_e32 v229, 4, v229
	v_lshl_add_u32 v229, v226, 8, v229
	v_add_u32_e32 v229, s14, v229
	v_or_b32_e32 v230, 8, v225
	v_xor_b32_e32 v230, v230, v227
	v_lshlrev_b32_e32 v230, 4, v230
	v_lshl_add_u32 v230, v226, 8, v230
	v_add_u32_e32 v230, s14, v230
	v_or_b32_e32 v231, 12, v225
	v_xor_b32_e32 v231, v231, v227
	v_lshlrev_b32_e32 v231, 4, v231
	v_lshl_add_u32 v231, v226, 8, v231
	v_add_u32_e32 v231, s14, v231
	ds_write_b128 v228, v[6:9] offset:0
	ds_write_b128 v229, v[34:37] offset:0
	ds_write_b128 v230, v[38:41] offset:0
	ds_write_b128 v231, v[30:33] offset:0
	ds_write_b128 v228, v[42:45] offset:4096
	ds_write_b128 v229, v[46:49] offset:4096
	ds_write_b128 v230, v[54:57] offset:4096
	ds_write_b128 v231, v[26:29] offset:4096
	ds_write_b128 v228, v[50:53] offset:8192
	ds_write_b128 v229, v[62:65] offset:8192
	ds_write_b128 v230, v[58:61] offset:8192
	ds_write_b128 v231, v[14:17] offset:8192
	ds_write_b128 v228, v[22:25] offset:12288
	ds_write_b128 v229, v[18:21] offset:12288
	ds_write_b128 v230, v[10:13] offset:12288
	ds_write_b128 v231, v[2:5] offset:12288
	s_waitcnt lgkmcnt(0)
	ds_read_b128 v[66:69], v232 offset:0
	ds_read_b128 v[70:73], v232 offset:1024
	ds_read_b128 v[74:77], v232 offset:2048
	ds_read_b128 v[78:81], v232 offset:3072
	ds_read_b128 v[82:85], v232 offset:4096
	ds_read_b128 v[86:89], v232 offset:5120
	ds_read_b128 v[90:93], v232 offset:6144
	ds_read_b128 v[94:97], v232 offset:7168
	s_waitcnt lgkmcnt(7)
	global_store_dwordx4 v233, v[66:69], s[92:93]
	v_add_u32_e32 v233, s49, v233
	s_waitcnt lgkmcnt(6)
	global_store_dwordx4 v233, v[70:73], s[92:93]
	v_add_u32_e32 v233, s49, v233
	s_waitcnt lgkmcnt(5)
	global_store_dwordx4 v233, v[74:77], s[92:93]
	v_add_u32_e32 v233, s49, v233
	s_waitcnt lgkmcnt(4)
	global_store_dwordx4 v233, v[78:81], s[92:93]
	v_add_u32_e32 v233, s49, v233
	s_waitcnt lgkmcnt(3)
	global_store_dwordx4 v233, v[82:85], s[92:93]
	v_add_u32_e32 v233, s49, v233
	s_waitcnt lgkmcnt(2)
	global_store_dwordx4 v233, v[86:89], s[92:93]
	v_add_u32_e32 v233, s49, v233
	s_waitcnt lgkmcnt(1)
	global_store_dwordx4 v233, v[90:93], s[92:93]
	v_add_u32_e32 v233, s49, v233
	s_waitcnt lgkmcnt(0)
	global_store_dwordx4 v233, v[94:97], s[92:93]
	v_add_u32_e32 v233, s49, v233
	s_nop 1
	ds_read_b128 v[66:69], v232 offset:8192
	ds_read_b128 v[70:73], v232 offset:9216
	ds_read_b128 v[74:77], v232 offset:10240
	ds_read_b128 v[78:81], v232 offset:11264
	ds_read_b128 v[82:85], v232 offset:12288
	ds_read_b128 v[86:89], v232 offset:13312
	ds_read_b128 v[90:93], v232 offset:14336
	ds_read_b128 v[94:97], v232 offset:15360
	s_waitcnt lgkmcnt(7)
	global_store_dwordx4 v233, v[66:69], s[92:93]
	v_add_u32_e32 v233, s49, v233
	s_waitcnt lgkmcnt(6)
	global_store_dwordx4 v233, v[70:73], s[92:93]
	v_add_u32_e32 v233, s49, v233
	s_waitcnt lgkmcnt(5)
	global_store_dwordx4 v233, v[74:77], s[92:93]
	v_add_u32_e32 v233, s49, v233
	s_waitcnt lgkmcnt(4)
	global_store_dwordx4 v233, v[78:81], s[92:93]
	v_add_u32_e32 v233, s49, v233
	s_waitcnt lgkmcnt(3)
	global_store_dwordx4 v233, v[82:85], s[92:93]
	v_add_u32_e32 v233, s49, v233
	s_waitcnt lgkmcnt(2)
	global_store_dwordx4 v233, v[86:89], s[92:93]
	v_add_u32_e32 v233, s49, v233
	s_waitcnt lgkmcnt(1)
	global_store_dwordx4 v233, v[90:93], s[92:93]
	v_add_u32_e32 v233, s49, v233
	s_waitcnt lgkmcnt(0)
	global_store_dwordx4 v233, v[94:97], s[92:93]
	v_add_u32_e32 v233, s49, v233
	s_nop 1
.Lipe_noO:
	s_cmp_lg_u32 s16, 0
	s_cbranch_scc0 .LBB0_345
	s_cmp_lt_u32 s20, 4
	s_cselect_b32 s22, 1, 0
	s_andn2_b32 s22, s22, s19
	s_cmp_lg_u32 s22, 0
	s_cbranch_scc0 .Lipe_norope
	s_add_u32 s22, s94, 0x11e58000
	s_addc_u32 s23, s95, 0
	s_add_u32 s48, s22, 0x1000
	s_addc_u32 s49, s23, 0
	v_add_u32_e32 v233, 0, v226
	v_add_u32_e32 v233, s46, v233
	v_lshrrev_b32_e32 v234, 6, v233
	v_and_b32_e32 v235, 63, v233
	v_lshlrev_b32_e32 v234, 6, v234
	v_lshlrev_b32_e32 v235, 6, v235
	v_lshl_add_u32 v234, v225, 4, v234
	v_lshl_add_u32 v235, v225, 4, v235
	global_load_dwordx4 v[66:69], v234, s[22:23]
	global_load_dwordx4 v[70:73], v234, s[48:49]
	global_load_dwordx4 v[74:77], v235, s[22:23]
	global_load_dwordx4 v[78:81], v235, s[48:49]
	s_waitcnt vmcnt(0)
	v_mul_f32_e32 v82, v6, v66
	v_mul_f32_e32 v86, v34, v66
	v_mul_f32_e32 v83, v7, v67
	v_mul_f32_e32 v87, v35, v67
	v_mul_f32_e32 v84, v8, v68
	v_mul_f32_e32 v88, v36, v68
	v_mul_f32_e32 v85, v9, v69
	v_mul_f32_e32 v89, v37, v69
	v_fma_f32 v82, -v34, v70, v82
	v_fma_f32 v86, v6, v70, v86
	v_fma_f32 v83, -v35, v71, v83
	v_fma_f32 v87, v7, v71, v87
	v_fma_f32 v84, -v36, v72, v84
	v_fma_f32 v88, v8, v72, v88
	v_fma_f32 v85, -v37, v73, v85
	v_fma_f32 v89, v9, v73, v89
	v_mov_b32_e32 v6, v82
	v_mov_b32_e32 v34, v86
	v_mov_b32_e32 v7, v83
	v_mov_b32_e32 v35, v87
	v_mov_b32_e32 v8, v84
	v_mov_b32_e32 v36, v88
	v_mov_b32_e32 v9, v85
	v_mov_b32_e32 v37, v89
	v_mul_f32_e32 v82, v38, v74
	v_mul_f32_e32 v86, v30, v74
	v_mul_f32_e32 v83, v39, v75
	v_mul_f32_e32 v87, v31, v75
	v_mul_f32_e32 v84, v40, v76
	v_mul_f32_e32 v88, v32, v76
	v_mul_f32_e32 v85, v41, v77
	v_mul_f32_e32 v89, v33, v77
	v_fma_f32 v82, -v30, v78, v82
	v_fma_f32 v86, v38, v78, v86
	v_fma_f32 v83, -v31, v79, v83
	v_fma_f32 v87, v39, v79, v87
	v_fma_f32 v84, -v32, v80, v84
	v_fma_f32 v88, v40, v80, v88
	v_fma_f32 v85, -v33, v81, v85
	v_fma_f32 v89, v41, v81, v89
	v_mov_b32_e32 v38, v82
	v_mov_b32_e32 v30, v86
	v_mov_b32_e32 v39, v83
	v_mov_b32_e32 v31, v87
	v_mov_b32_e32 v40, v84
	v_mov_b32_e32 v32, v88
	v_mov_b32_e32 v41, v85
	v_mov_b32_e32 v33, v89
	v_add_u32_e32 v233, 16, v226
	v_add_u32_e32 v233, s46, v233
	v_lshrrev_b32_e32 v234, 6, v233
	v_and_b32_e32 v235, 63, v233
	v_lshlrev_b32_e32 v234, 6, v234
	v_lshlrev_b32_e32 v235, 6, v235
	v_lshl_add_u32 v234, v225, 4, v234
	v_lshl_add_u32 v235, v225, 4, v235
	global_load_dwordx4 v[66:69], v234, s[22:23]
	global_load_dwordx4 v[70:73], v234, s[48:49]
	global_load_dwordx4 v[74:77], v235, s[22:23]
	global_load_dwordx4 v[78:81], v235, s[48:49]
	s_waitcnt vmcnt(0)
	v_mul_f32_e32 v82, v42, v66
	v_mul_f32_e32 v86, v46, v66
	v_mul_f32_e32 v83, v43, v67
	v_mul_f32_e32 v87, v47, v67
	v_mul_f32_e32 v84, v44, v68
	v_mul_f32_e32 v88, v48, v68
	v_mul_f32_e32 v85, v45, v69
	v_mul_f32_e32 v89, v49, v69
	v_fma_f32 v82, -v46, v70, v82
	v_fma_f32 v86, v42, v70, v86
	v_fma_f32 v83, -v47, v71, v83
	v_fma_f32 v87, v43, v71, v87
	v_fma_f32 v84, -v48, v72, v84
	v_fma_f32 v88, v44, v72, v88
	v_fma_f32 v85, -v49, v73, v85
	v_fma_f32 v89, v45, v73, v89
	v_mov_b32_e32 v42, v82
	v_mov_b32_e32 v46, v86
	v_mov_b32_e32 v43, v83
	v_mov_b32_e32 v47, v87
	v_mov_b32_e32 v44, v84
	v_mov_b32_e32 v48, v88
	v_mov_b32_e32 v45, v85
	v_mov_b32_e32 v49, v89
	v_mul_f32_e32 v82, v54, v74
	v_mul_f32_e32 v86, v26, v74
	v_mul_f32_e32 v83, v55, v75
	v_mul_f32_e32 v87, v27, v75
	v_mul_f32_e32 v84, v56, v76
	v_mul_f32_e32 v88, v28, v76
	v_mul_f32_e32 v85, v57, v77
	v_mul_f32_e32 v89, v29, v77
	v_fma_f32 v82, -v26, v78, v82
	v_fma_f32 v86, v54, v78, v86
	v_fma_f32 v83, -v27, v79, v83
	v_fma_f32 v87, v55, v79, v87
	v_fma_f32 v84, -v28, v80, v84
	v_fma_f32 v88, v56, v80, v88
	v_fma_f32 v85, -v29, v81, v85
	v_fma_f32 v89, v57, v81, v89
	v_mov_b32_e32 v54, v82
	v_mov_b32_e32 v26, v86
	v_mov_b32_e32 v55, v83
	v_mov_b32_e32 v27, v87
	v_mov_b32_e32 v56, v84
	v_mov_b32_e32 v28, v88
	v_mov_b32_e32 v57, v85
	v_mov_b32_e32 v29, v89
	v_add_u32_e32 v233, 32, v226
	v_add_u32_e32 v233, s46, v233
	v_lshrrev_b32_e32 v234, 6, v233
	v_and_b32_e32 v235, 63, v233
	v_lshlrev_b32_e32 v234, 6, v234
	v_lshlrev_b32_e32 v235, 6, v235
	v_lshl_add_u32 v234, v225, 4, v234
	v_lshl_add_u32 v235, v225, 4, v235
	global_load_dwordx4 v[66:69], v234, s[22:23]
	global_load_dwordx4 v[70:73], v234, s[48:49]
	global_load_dwordx4 v[74:77], v235, s[22:23]
	global_load_dwordx4 v[78:81], v235, s[48:49]
	s_waitcnt vmcnt(0)
	v_mul_f32_e32 v82, v50, v66
	v_mul_f32_e32 v86, v62, v66
	v_mul_f32_e32 v83, v51, v67
	v_mul_f32_e32 v87, v63, v67
	v_mul_f32_e32 v84, v52, v68
	v_mul_f32_e32 v88, v64, v68
	v_mul_f32_e32 v85, v53, v69
	v_mul_f32_e32 v89, v65, v69
	v_fma_f32 v82, -v62, v70, v82
	v_fma_f32 v86, v50, v70, v86
	v_fma_f32 v83, -v63, v71, v83
	v_fma_f32 v87, v51, v71, v87
	v_fma_f32 v84, -v64, v72, v84
	v_fma_f32 v88, v52, v72, v88
	v_fma_f32 v85, -v65, v73, v85
	v_fma_f32 v89, v53, v73, v89
	v_mov_b32_e32 v50, v82
	v_mov_b32_e32 v62, v86
	v_mov_b32_e32 v51, v83
	v_mov_b32_e32 v63, v87
	v_mov_b32_e32 v52, v84
	v_mov_b32_e32 v64, v88
	v_mov_b32_e32 v53, v85
	v_mov_b32_e32 v65, v89
	v_mul_f32_e32 v82, v58, v74
	v_mul_f32_e32 v86, v14, v74
	v_mul_f32_e32 v83, v59, v75
	v_mul_f32_e32 v87, v15, v75
	v_mul_f32_e32 v84, v60, v76
	v_mul_f32_e32 v88, v16, v76
	v_mul_f32_e32 v85, v61, v77
	v_mul_f32_e32 v89, v17, v77
	v_fma_f32 v82, -v14, v78, v82
	v_fma_f32 v86, v58, v78, v86
	v_fma_f32 v83, -v15, v79, v83
	v_fma_f32 v87, v59, v79, v87
	v_fma_f32 v84, -v16, v80, v84
	v_fma_f32 v88, v60, v80, v88
	v_fma_f32 v85, -v17, v81, v85
	v_fma_f32 v89, v61, v81, v89
	v_mov_b32_e32 v58, v82
	v_mov_b32_e32 v14, v86
	v_mov_b32_e32 v59, v83
	v_mov_b32_e32 v15, v87
	v_mov_b32_e32 v60, v84
	v_mov_b32_e32 v16, v88
	v_mov_b32_e32 v61, v85
	v_mov_b32_e32 v17, v89
	v_add_u32_e32 v233, 48, v226
	v_add_u32_e32 v233, s46, v233
	v_lshrrev_b32_e32 v234, 6, v233
	v_and_b32_e32 v235, 63, v233
	v_lshlrev_b32_e32 v234, 6, v234
	v_lshlrev_b32_e32 v235, 6, v235
	v_lshl_add_u32 v234, v225, 4, v234
	v_lshl_add_u32 v235, v225, 4, v235
	global_load_dwordx4 v[66:69], v234, s[22:23]
	global_load_dwordx4 v[70:73], v234, s[48:49]
	global_load_dwordx4 v[74:77], v235, s[22:23]
	global_load_dwordx4 v[78:81], v235, s[48:49]
	s_waitcnt vmcnt(0)
	v_mul_f32_e32 v82, v22, v66
	v_mul_f32_e32 v86, v18, v66
	v_mul_f32_e32 v83, v23, v67
	v_mul_f32_e32 v87, v19, v67
	v_mul_f32_e32 v84, v24, v68
	v_mul_f32_e32 v88, v20, v68
	v_mul_f32_e32 v85, v25, v69
	v_mul_f32_e32 v89, v21, v69
	v_fma_f32 v82, -v18, v70, v82
	v_fma_f32 v86, v22, v70, v86
	v_fma_f32 v83, -v19, v71, v83
	v_fma_f32 v87, v23, v71, v87
	v_fma_f32 v84, -v20, v72, v84
	v_fma_f32 v88, v24, v72, v88
	v_fma_f32 v85, -v21, v73, v85
	v_fma_f32 v89, v25, v73, v89
	v_mov_b32_e32 v22, v82
	v_mov_b32_e32 v18, v86
	v_mov_b32_e32 v23, v83
	v_mov_b32_e32 v19, v87
	v_mov_b32_e32 v24, v84
	v_mov_b32_e32 v20, v88
	v_mov_b32_e32 v25, v85
	v_mov_b32_e32 v21, v89
	v_mul_f32_e32 v82, v10, v74
	v_mul_f32_e32 v86, v2, v74
	v_mul_f32_e32 v83, v11, v75
	v_mul_f32_e32 v87, v3, v75
	v_mul_f32_e32 v84, v12, v76
	v_mul_f32_e32 v88, v4, v76
	v_mul_f32_e32 v85, v13, v77
	v_mul_f32_e32 v89, v5, v77
	v_fma_f32 v82, -v2, v78, v82
	v_fma_f32 v86, v10, v78, v86
	v_fma_f32 v83, -v3, v79, v83
	v_fma_f32 v87, v11, v79, v87
	v_fma_f32 v84, -v4, v80, v84
	v_fma_f32 v88, v12, v80, v88
	v_fma_f32 v85, -v5, v81, v85
	v_fma_f32 v89, v13, v81, v89
	v_mov_b32_e32 v10, v82
	v_mov_b32_e32 v2, v86
	v_mov_b32_e32 v11, v83
	v_mov_b32_e32 v3, v87
	v_mov_b32_e32 v12, v84
	v_mov_b32_e32 v4, v88
	v_mov_b32_e32 v13, v85
	v_mov_b32_e32 v5, v89
.Lipe_norope:
	v_and_b32_e32 v227, 7, v226
	v_lshlrev_b32_e32 v227, 1, v227
	v_or_b32_e32 v228, 0, v225
	v_xor_b32_e32 v228, v228, v227
	v_lshlrev_b32_e32 v228, 3, v228
	v_lshl_add_u32 v228, v226, 7, v228
	v_add_u32_e32 v228, s14, v228
	v_or_b32_e32 v229, 4, v225
	v_xor_b32_e32 v229, v229, v227
	v_lshlrev_b32_e32 v229, 3, v229
	v_lshl_add_u32 v229, v226, 7, v229
	v_add_u32_e32 v229, s14, v229
	v_or_b32_e32 v230, 8, v225
	v_xor_b32_e32 v230, v230, v227
	v_lshlrev_b32_e32 v230, 3, v230
	v_lshl_add_u32 v230, v226, 7, v230
	v_add_u32_e32 v230, s14, v230
	v_or_b32_e32 v231, 12, v225
	v_xor_b32_e32 v231, v231, v227
	v_lshlrev_b32_e32 v231, 3, v231
	v_lshl_add_u32 v231, v226, 7, v231
	v_add_u32_e32 v231, s14, v231
	v_add_u32_e32 v233, s13, v236
	v_mul_u32_u24_e32 v233, 0x1a20, v233
	v_lshl_add_u32 v233, v237, 4, v233
	s_lshl_b32 s16, s6, 1
	v_add_u32_e32 v233, s16, v233
	s_add_u32 s16, s94, 0x8748000
	s_addc_u32 s17, s95, 0
	v_cvt_pk_bf16_f32 v6, v6, v7
	v_cvt_pk_bf16_f32 v7, v8, v9
	ds_write_b64 v228, v[6:7] offset:0
	v_cvt_pk_bf16_f32 v34, v34, v35
	v_cvt_pk_bf16_f32 v35, v36, v37
	ds_write_b64 v229, v[34:35] offset:0
	v_cvt_pk_bf16_f32 v38, v38, v39
	v_cvt_pk_bf16_f32 v39, v40, v41
	ds_write_b64 v230, v[38:39] offset:0
	v_cvt_pk_bf16_f32 v30, v30, v31
	v_cvt_pk_bf16_f32 v31, v32, v33
	ds_write_b64 v231, v[30:31] offset:0
	v_cvt_pk_bf16_f32 v42, v42, v43
	v_cvt_pk_bf16_f32 v43, v44, v45
	ds_write_b64 v228, v[42:43] offset:2048
	v_cvt_pk_bf16_f32 v46, v46, v47
	v_cvt_pk_bf16_f32 v47, v48, v49
	ds_write_b64 v229, v[46:47] offset:2048
	v_cvt_pk_bf16_f32 v54, v54, v55
	v_cvt_pk_bf16_f32 v55, v56, v57
	ds_write_b64 v230, v[54:55] offset:2048
	v_cvt_pk_bf16_f32 v26, v26, v27
	v_cvt_pk_bf16_f32 v27, v28, v29
	ds_write_b64 v231, v[26:27] offset:2048
	v_cvt_pk_bf16_f32 v50, v50, v51
	v_cvt_pk_bf16_f32 v51, v52, v53
	ds_write_b64 v228, v[50:51] offset:4096
	v_cvt_pk_bf16_f32 v62, v62, v63
	v_cvt_pk_bf16_f32 v63, v64, v65
	ds_write_b64 v229, v[62:63] offset:4096
	v_cvt_pk_bf16_f32 v58, v58, v59
	v_cvt_pk_bf16_f32 v59, v60, v61
	ds_write_b64 v230, v[58:59] offset:4096
	v_cvt_pk_bf16_f32 v14, v14, v15
	v_cvt_pk_bf16_f32 v15, v16, v17
	ds_write_b64 v231, v[14:15] offset:4096
	v_cvt_pk_bf16_f32 v22, v22, v23
	v_cvt_pk_bf16_f32 v23, v24, v25
	ds_write_b64 v228, v[22:23] offset:6144
	v_cvt_pk_bf16_f32 v18, v18, v19
	v_cvt_pk_bf16_f32 v19, v20, v21
	ds_write_b64 v229, v[18:19] offset:6144
	v_cvt_pk_bf16_f32 v10, v10, v11
	v_cvt_pk_bf16_f32 v11, v12, v13
	ds_write_b64 v230, v[10:11] offset:6144
	v_cvt_pk_bf16_f32 v2, v2, v3
	v_cvt_pk_bf16_f32 v3, v4, v5
	ds_write_b64 v231, v[2:3] offset:6144
	s_waitcnt lgkmcnt(0)
	ds_read_b128 v[66:69], v232 offset:0
	ds_read_b128 v[70:73], v232 offset:1024
	ds_read_b128 v[74:77], v232 offset:2048
	ds_read_b128 v[78:81], v232 offset:3072
	ds_read_b128 v[82:85], v232 offset:4096
	ds_read_b128 v[86:89], v232 offset:5120
	ds_read_b128 v[90:93], v232 offset:6144
	ds_read_b128 v[94:97], v232 offset:7168
	s_waitcnt lgkmcnt(7)
	global_store_dwordx4 v233, v[66:69], s[16:17]
	s_waitcnt lgkmcnt(6)
	v_add_u32_e32 v235, 0xd100, v233
	global_store_dwordx4 v235, v[70:73], s[16:17]
	s_waitcnt lgkmcnt(5)
	v_add_u32_e32 v235, 0x1a200, v233
	global_store_dwordx4 v235, v[74:77], s[16:17]
	s_waitcnt lgkmcnt(4)
	v_add_u32_e32 v235, 0x27300, v233
	global_store_dwordx4 v235, v[78:81], s[16:17]
	s_waitcnt lgkmcnt(3)
	v_add_u32_e32 v235, 0x34400, v233
	global_store_dwordx4 v235, v[82:85], s[16:17]
	s_waitcnt lgkmcnt(2)
	v_add_u32_e32 v235, 0x41500, v233
	global_store_dwordx4 v235, v[86:89], s[16:17]
	s_waitcnt lgkmcnt(1)
	v_add_u32_e32 v235, 0x4e600, v233
	global_store_dwordx4 v235, v[90:93], s[16:17]
	s_waitcnt lgkmcnt(0)
	v_add_u32_e32 v235, 0x5b700, v233
	global_store_dwordx4 v235, v[94:97], s[16:17]
	s_branch .LBB0_345
